# v54 + GEMM K-loop: LDS-read drain moved from before the pre-MFMA barrier to after it (the wait after the barrier was already there)
# baseline (speedup 1.0000x reference)
.LBB0_64:
	s_add_i32 s33, s42, 2
	s_add_u32 s46, s40, 0x80
	s_addc_u32 s43, s41, 0
	s_add_i32 s80, 0, 0x10000
	s_cmp_eq_u32 s84, s42
	s_cselect_b32 s43, s1, s43
	s_cselect_b32 s42, s0, s46
	s_cselect_b32 s47, s75, vcc_hi
	s_cselect_b32 s46, s74, vcc_lo
	s_add_i32 s5, 0, 0x14000
	v_add_u32_e32 v140, s80, v185
	v_add_u32_e32 v166, s5, v185
	ds_read_b128 v[128:131], v140
	ds_read_b128 v[132:135], v140 offset:1024
	ds_read_b128 v[136:139], v140 offset:2048
	ds_read_b128 v[140:143], v140 offset:3072
	ds_read_b128 v[144:147], v166
	ds_read_b128 v[148:151], v166 offset:1024
	ds_read_b128 v[152:155], v166 offset:2048
	ds_read_b128 v[166:169], v166 offset:3072
	v_lshl_add_u64 v[182:183], s[40:41], 0, v[162:163]
	s_add_i32 m0, s28, 0xc000
	ds_read_b128 v[170:173], v188
	ds_read_b128 v[174:177], v188 offset:1024
	ds_read_b128 v[178:181], v188 offset:2048
	ds_read_b128 v[214:217], v188 offset:3072
	ds_read_b128 v[218:221], v188 offset:4096
	ds_read_b128 v[222:225], v188 offset:5120
	ds_read_b128 v[226:229], v188 offset:6144
	ds_read_b128 v[230:233], v188 offset:7168
	global_load_lds_dwordx4 v[182:183], off
	v_lshl_add_u64 v[182:183], s[40:41], 0, v[164:165]
	s_add_i32 m0, s28, 0xe000
	s_nop 0
	global_load_lds_dwordx4 v[182:183], off
	s_waitcnt vmcnt(8)
	s_barrier
	s_waitcnt lgkmcnt(0)
	v_mfma_f32_16x16x32_bf16 v[124:127], v[128:131], v[170:173], v[124:127]
	v_mfma_f32_16x16x32_bf16 v[120:123], v[136:139], v[170:173], v[120:123]
	v_mfma_f32_16x16x32_bf16 v[108:111], v[128:131], v[178:181], v[108:111]
	v_mfma_f32_16x16x32_bf16 v[104:107], v[136:139], v[178:181], v[104:107]
	v_mfma_f32_16x16x32_bf16 v[92:95], v[128:131], v[218:221], v[92:95]
	v_mfma_f32_16x16x32_bf16 v[88:91], v[136:139], v[218:221], v[88:91]
	v_mfma_f32_16x16x32_bf16 v[76:79], v[128:131], v[226:229], v[76:79]
	v_mfma_f32_16x16x32_bf16 v[72:75], v[136:139], v[226:229], v[72:75]
	v_mfma_f32_16x16x32_bf16 v[124:127], v[132:135], v[174:177], v[124:127]
	v_mfma_f32_16x16x32_bf16 v[120:123], v[140:143], v[174:177], v[120:123]
	v_mfma_f32_16x16x32_bf16 v[108:111], v[132:135], v[214:217], v[108:111]
	v_mfma_f32_16x16x32_bf16 v[104:107], v[140:143], v[214:217], v[104:107]
	v_mfma_f32_16x16x32_bf16 v[92:95], v[132:135], v[222:225], v[92:95]
	v_mfma_f32_16x16x32_bf16 v[88:91], v[140:143], v[222:225], v[88:91]
	v_mfma_f32_16x16x32_bf16 v[76:79], v[132:135], v[230:233], v[76:79]
	v_mfma_f32_16x16x32_bf16 v[72:75], v[140:143], v[230:233], v[72:75]
	v_mfma_f32_16x16x32_bf16 v[116:119], v[144:147], v[170:173], v[116:119]
	v_mfma_f32_16x16x32_bf16 v[112:115], v[152:155], v[170:173], v[112:115]
	v_mfma_f32_16x16x32_bf16 v[100:103], v[144:147], v[178:181], v[100:103]
	v_mfma_f32_16x16x32_bf16 v[96:99], v[152:155], v[178:181], v[96:99]
	v_mfma_f32_16x16x32_bf16 v[84:87], v[144:147], v[218:221], v[84:87]
	v_mfma_f32_16x16x32_bf16 v[80:83], v[152:155], v[218:221], v[80:83]
	v_mfma_f32_16x16x32_bf16 v[68:71], v[144:147], v[226:229], v[68:71]
	v_mfma_f32_16x16x32_bf16 v[64:67], v[152:155], v[226:229], v[64:67]
	v_mfma_f32_16x16x32_bf16 v[116:119], v[148:151], v[174:177], v[116:119]
	v_mfma_f32_16x16x32_bf16 v[112:115], v[166:169], v[174:177], v[112:115]
	v_mfma_f32_16x16x32_bf16 v[100:103], v[148:151], v[214:217], v[100:103]
	v_mfma_f32_16x16x32_bf16 v[96:99], v[166:169], v[214:217], v[96:99]
	v_mfma_f32_16x16x32_bf16 v[84:87], v[148:151], v[222:225], v[84:87]
	v_mfma_f32_16x16x32_bf16 v[80:83], v[166:169], v[222:225], v[80:83]
	v_mfma_f32_16x16x32_bf16 v[68:71], v[148:151], v[230:233], v[68:71]
	v_mfma_f32_16x16x32_bf16 v[64:67], v[166:169], v[230:233], v[64:67]
	s_barrier
	s_add_i32 s80, s80, s27
	v_lshl_add_u64 v[182:183], s[46:47], 0, v[192:193]
	s_mov_b32 m0, s80
	ds_read_b128 v[170:173], v188 offset:16384
	ds_read_b128 v[174:177], v188 offset:17408
	ds_read_b128 v[178:181], v188 offset:18432
	ds_read_b128 v[214:217], v188 offset:19456
	ds_read_b128 v[218:221], v188 offset:20480
	ds_read_b128 v[222:225], v188 offset:21504
	ds_read_b128 v[226:229], v188 offset:22528
	ds_read_b128 v[230:233], v188 offset:23552
	global_load_lds_dwordx4 v[182:183], off
	s_add_i32 m0, s80, 0x2000
	v_lshl_add_u64 v[190:191], s[46:47], 0, v[160:161]
	s_add_u32 s46, s46, s30
	s_addc_u32 s47, s47, 0
	s_add_i32 s5, s5, s27
	global_load_lds_dwordx4 v[190:191], off
	v_lshl_add_u64 v[200:201], s[46:47], 0, v[192:193]
	s_mov_b32 m0, s5
	v_lshl_add_u64 v[234:235], s[46:47], 0, v[160:161]
	global_load_lds_dwordx4 v[200:201], off
	s_add_i32 m0, s5, 0x2000
	v_lshl_add_u64 v[236:237], s[42:43], 0, v[156:157]
	global_load_lds_dwordx4 v[234:235], off
	s_mov_b32 m0, s28
	v_lshl_add_u64 v[238:239], s[42:43], 0, v[158:159]
	global_load_lds_dwordx4 v[236:237], off
	s_mov_b32 m0, s69
	s_nop 0
	global_load_lds_dwordx4 v[238:239], off
	s_waitcnt vmcnt(8)
	s_barrier
	s_waitcnt lgkmcnt(0)
	v_mfma_f32_16x16x32_bf16 v[60:63], v[128:131], v[170:173], v[60:63]
	v_mfma_f32_16x16x32_bf16 v[56:59], v[136:139], v[170:173], v[56:59]
	v_mfma_f32_16x16x32_bf16 v[44:47], v[128:131], v[178:181], v[44:47]
	v_mfma_f32_16x16x32_bf16 v[40:43], v[136:139], v[178:181], v[40:43]
	v_mfma_f32_16x16x32_bf16 v[28:31], v[128:131], v[218:221], v[28:31]
	v_mfma_f32_16x16x32_bf16 v[24:27], v[136:139], v[218:221], v[24:27]
	v_mfma_f32_16x16x32_bf16 v[12:15], v[128:131], v[226:229], v[12:15]
	v_mfma_f32_16x16x32_bf16 v[8:11], v[136:139], v[226:229], v[8:11]
	v_mfma_f32_16x16x32_bf16 v[60:63], v[132:135], v[174:177], v[60:63]
	v_mfma_f32_16x16x32_bf16 v[56:59], v[140:143], v[174:177], v[56:59]
	v_mfma_f32_16x16x32_bf16 v[44:47], v[132:135], v[214:217], v[44:47]
	v_mfma_f32_16x16x32_bf16 v[40:43], v[140:143], v[214:217], v[40:43]
	v_mfma_f32_16x16x32_bf16 v[28:31], v[132:135], v[222:225], v[28:31]
	v_mfma_f32_16x16x32_bf16 v[24:27], v[140:143], v[222:225], v[24:27]
	v_mfma_f32_16x16x32_bf16 v[12:15], v[132:135], v[230:233], v[12:15]
	v_mfma_f32_16x16x32_bf16 v[8:11], v[140:143], v[230:233], v[8:11]
	v_mfma_f32_16x16x32_bf16 v[52:55], v[144:147], v[170:173], v[52:55]
	v_mfma_f32_16x16x32_bf16 v[48:51], v[152:155], v[170:173], v[48:51]
	v_mfma_f32_16x16x32_bf16 v[36:39], v[144:147], v[178:181], v[36:39]
	v_mfma_f32_16x16x32_bf16 v[32:35], v[152:155], v[178:181], v[32:35]
	v_mfma_f32_16x16x32_bf16 v[20:23], v[144:147], v[218:221], v[20:23]
	v_mfma_f32_16x16x32_bf16 v[16:19], v[152:155], v[218:221], v[16:19]
	v_mfma_f32_16x16x32_bf16 v[4:7], v[144:147], v[226:229], v[4:7]
	v_mfma_f32_16x16x32_bf16 v[0:3], v[152:155], v[226:229], v[0:3]
	v_mfma_f32_16x16x32_bf16 v[52:55], v[148:151], v[174:177], v[52:55]
	v_mfma_f32_16x16x32_bf16 v[48:51], v[166:169], v[174:177], v[48:51]
	v_mfma_f32_16x16x32_bf16 v[36:39], v[148:151], v[214:217], v[36:39]
	v_mfma_f32_16x16x32_bf16 v[32:35], v[166:169], v[214:217], v[32:35]
	v_mfma_f32_16x16x32_bf16 v[20:23], v[148:151], v[222:225], v[20:23]
	v_mfma_f32_16x16x32_bf16 v[16:19], v[166:169], v[222:225], v[16:19]
	v_mfma_f32_16x16x32_bf16 v[4:7], v[148:151], v[230:233], v[4:7]
	v_mfma_f32_16x16x32_bf16 v[0:3], v[166:169], v[230:233], v[0:3]
	s_barrier
.Lmy_sp3:
	s_add_i32 s5, 0, 0x18000
	s_add_i32 s46, 0, 0x1c000
	v_add_u32_e32 v140, s5, v185
	v_add_u32_e32 v166, s46, v185
	ds_read_b128 v[128:131], v140
	ds_read_b128 v[132:135], v140 offset:1024
	ds_read_b128 v[136:139], v140 offset:2048
	ds_read_b128 v[140:143], v140 offset:3072
	ds_read_b128 v[144:147], v166
	ds_read_b128 v[148:151], v166 offset:1024
	ds_read_b128 v[152:155], v166 offset:2048
	ds_read_b128 v[166:169], v166 offset:3072
	s_add_u32 s42, s42, s30
	s_addc_u32 s43, s43, 0
	s_mov_b32 m0, s72
	v_lshl_add_u64 v[240:241], s[42:43], 0, v[156:157]
	ds_read_b128 v[170:173], v188 offset:32768
	ds_read_b128 v[174:177], v188 offset:33792
	ds_read_b128 v[178:181], v188 offset:34816
	ds_read_b128 v[214:217], v188 offset:35840
	ds_read_b128 v[218:221], v188 offset:36864
	ds_read_b128 v[222:225], v188 offset:37888
	ds_read_b128 v[226:229], v188 offset:38912
	ds_read_b128 v[230:233], v188 offset:39936
	global_load_lds_dwordx4 v[240:241], off
	v_lshl_add_u64 v[240:241], s[42:43], 0, v[158:159]
	s_mov_b32 m0, s76
	s_nop 0
	global_load_lds_dwordx4 v[240:241], off
	s_waitcnt vmcnt(8)
	s_barrier
	s_waitcnt lgkmcnt(0)
	v_mfma_f32_16x16x32_bf16 v[124:127], v[128:131], v[170:173], v[124:127]
	v_mfma_f32_16x16x32_bf16 v[120:123], v[136:139], v[170:173], v[120:123]
	v_mfma_f32_16x16x32_bf16 v[108:111], v[128:131], v[178:181], v[108:111]
	v_mfma_f32_16x16x32_bf16 v[104:107], v[136:139], v[178:181], v[104:107]
	v_mfma_f32_16x16x32_bf16 v[92:95], v[128:131], v[218:221], v[92:95]
	v_mfma_f32_16x16x32_bf16 v[88:91], v[136:139], v[218:221], v[88:91]
	v_mfma_f32_16x16x32_bf16 v[76:79], v[128:131], v[226:229], v[76:79]
	v_mfma_f32_16x16x32_bf16 v[72:75], v[136:139], v[226:229], v[72:75]
	v_mfma_f32_16x16x32_bf16 v[124:127], v[132:135], v[174:177], v[124:127]
	v_mfma_f32_16x16x32_bf16 v[120:123], v[140:143], v[174:177], v[120:123]
	v_mfma_f32_16x16x32_bf16 v[108:111], v[132:135], v[214:217], v[108:111]
	v_mfma_f32_16x16x32_bf16 v[104:107], v[140:143], v[214:217], v[104:107]
	v_mfma_f32_16x16x32_bf16 v[92:95], v[132:135], v[222:225], v[92:95]
	v_mfma_f32_16x16x32_bf16 v[88:91], v[140:143], v[222:225], v[88:91]
	v_mfma_f32_16x16x32_bf16 v[76:79], v[132:135], v[230:233], v[76:79]
	v_mfma_f32_16x16x32_bf16 v[72:75], v[140:143], v[230:233], v[72:75]
	v_mfma_f32_16x16x32_bf16 v[116:119], v[144:147], v[170:173], v[116:119]
	v_mfma_f32_16x16x32_bf16 v[112:115], v[152:155], v[170:173], v[112:115]
	v_mfma_f32_16x16x32_bf16 v[100:103], v[144:147], v[178:181], v[100:103]
	v_mfma_f32_16x16x32_bf16 v[96:99], v[152:155], v[178:181], v[96:99]
	v_mfma_f32_16x16x32_bf16 v[84:87], v[144:147], v[218:221], v[84:87]
	v_mfma_f32_16x16x32_bf16 v[80:83], v[152:155], v[218:221], v[80:83]
	v_mfma_f32_16x16x32_bf16 v[68:71], v[144:147], v[226:229], v[68:71]
	v_mfma_f32_16x16x32_bf16 v[64:67], v[152:155], v[226:229], v[64:67]
	v_mfma_f32_16x16x32_bf16 v[116:119], v[148:151], v[174:177], v[116:119]
	v_mfma_f32_16x16x32_bf16 v[112:115], v[166:169], v[174:177], v[112:115]
	v_mfma_f32_16x16x32_bf16 v[100:103], v[148:151], v[214:217], v[100:103]
	v_mfma_f32_16x16x32_bf16 v[96:99], v[166:169], v[214:217], v[96:99]
	v_mfma_f32_16x16x32_bf16 v[84:87], v[148:151], v[222:225], v[84:87]
	v_mfma_f32_16x16x32_bf16 v[80:83], v[166:169], v[222:225], v[80:83]
	v_mfma_f32_16x16x32_bf16 v[68:71], v[148:151], v[230:233], v[68:71]
	v_mfma_f32_16x16x32_bf16 v[64:67], v[166:169], v[230:233], v[64:67]
	s_barrier
	s_add_i32 s5, s5, s27
	v_lshl_add_u64 v[182:183], v[182:183], 0, s[70:71]
	s_mov_b32 m0, s5
	ds_read_b128 v[170:173], v188 offset:49152
	ds_read_b128 v[174:177], v188 offset:50176
	ds_read_b128 v[178:181], v188 offset:51200
	ds_read_b128 v[214:217], v188 offset:52224
	ds_read_b128 v[218:221], v188 offset:53248
	ds_read_b128 v[222:225], v188 offset:54272
	ds_read_b128 v[226:229], v188 offset:55296
	ds_read_b128 v[230:233], v188 offset:56320
	global_load_lds_dwordx4 v[182:183], off
	v_lshl_add_u64 v[182:183], v[190:191], 0, s[70:71]
	s_add_i32 m0, s5, 0x2000
	s_add_i32 s5, s46, s27
	global_load_lds_dwordx4 v[182:183], off
	v_lshl_add_u64 v[182:183], v[200:201], 0, s[70:71]
	s_mov_b32 m0, s5
	s_nop 0
	global_load_lds_dwordx4 v[182:183], off
	v_lshl_add_u64 v[182:183], v[234:235], 0, s[70:71]
	s_add_i32 m0, s5, 0x2000
	s_nop 0
	global_load_lds_dwordx4 v[182:183], off
	v_lshl_add_u64 v[182:183], v[236:237], 0, s[70:71]
	s_mov_b32 m0, s81
	s_nop 0
	global_load_lds_dwordx4 v[182:183], off
	v_lshl_add_u64 v[182:183], v[238:239], 0, s[70:71]
	s_mov_b32 m0, s82
	s_nop 0
	global_load_lds_dwordx4 v[182:183], off
	s_waitcnt vmcnt(8)
	s_barrier
	s_waitcnt lgkmcnt(0)
	v_mfma_f32_16x16x32_bf16 v[60:63], v[128:131], v[170:173], v[60:63]
	v_mfma_f32_16x16x32_bf16 v[56:59], v[136:139], v[170:173], v[56:59]
	v_mfma_f32_16x16x32_bf16 v[44:47], v[128:131], v[178:181], v[44:47]
	v_mfma_f32_16x16x32_bf16 v[40:43], v[136:139], v[178:181], v[40:43]
	v_mfma_f32_16x16x32_bf16 v[28:31], v[128:131], v[218:221], v[28:31]
	v_mfma_f32_16x16x32_bf16 v[24:27], v[136:139], v[218:221], v[24:27]
	v_mfma_f32_16x16x32_bf16 v[12:15], v[128:131], v[226:229], v[12:15]
	v_mfma_f32_16x16x32_bf16 v[8:11], v[136:139], v[226:229], v[8:11]
	v_mfma_f32_16x16x32_bf16 v[60:63], v[132:135], v[174:177], v[60:63]
	v_mfma_f32_16x16x32_bf16 v[56:59], v[140:143], v[174:177], v[56:59]
	v_mfma_f32_16x16x32_bf16 v[44:47], v[132:135], v[214:217], v[44:47]
	v_mfma_f32_16x16x32_bf16 v[40:43], v[140:143], v[214:217], v[40:43]
	v_mfma_f32_16x16x32_bf16 v[28:31], v[132:135], v[222:225], v[28:31]
	v_mfma_f32_16x16x32_bf16 v[24:27], v[140:143], v[222:225], v[24:27]
	v_mfma_f32_16x16x32_bf16 v[12:15], v[132:135], v[230:233], v[12:15]
	v_mfma_f32_16x16x32_bf16 v[8:11], v[140:143], v[230:233], v[8:11]
	v_mfma_f32_16x16x32_bf16 v[52:55], v[144:147], v[170:173], v[52:55]
	v_mfma_f32_16x16x32_bf16 v[48:51], v[152:155], v[170:173], v[48:51]
	v_mfma_f32_16x16x32_bf16 v[36:39], v[144:147], v[178:181], v[36:39]
	v_mfma_f32_16x16x32_bf16 v[32:35], v[152:155], v[178:181], v[32:35]
	v_mfma_f32_16x16x32_bf16 v[20:23], v[144:147], v[218:221], v[20:23]
	v_mfma_f32_16x16x32_bf16 v[16:19], v[152:155], v[218:221], v[16:19]
	v_mfma_f32_16x16x32_bf16 v[4:7], v[144:147], v[226:229], v[4:7]
	v_mfma_f32_16x16x32_bf16 v[0:3], v[152:155], v[226:229], v[0:3]
	v_mfma_f32_16x16x32_bf16 v[52:55], v[148:151], v[174:177], v[52:55]
	v_mfma_f32_16x16x32_bf16 v[48:51], v[166:169], v[174:177], v[48:51]
	v_mfma_f32_16x16x32_bf16 v[36:39], v[148:151], v[214:217], v[36:39]
	v_mfma_f32_16x16x32_bf16 v[32:35], v[166:169], v[214:217], v[32:35]
	v_mfma_f32_16x16x32_bf16 v[20:23], v[148:151], v[222:225], v[20:23]
	v_mfma_f32_16x16x32_bf16 v[16:19], v[166:169], v[222:225], v[16:19]
	v_mfma_f32_16x16x32_bf16 v[4:7], v[148:151], v[230:233], v[4:7]
	v_mfma_f32_16x16x32_bf16 v[0:3], v[166:169], v[230:233], v[0:3]
	s_barrier
	s_add_u32 s40, s40, 0x100
	s_addc_u32 s41, s41, 0
	s_add_u32 vcc_lo, vcc_lo, 0x100
	s_addc_u32 vcc_hi, vcc_hi, 0
	s_cmp_ge_u32 s33, s78
	s_mov_b32 s42, s33
	s_cbranch_scc0 .LBB0_64
	s_and_b64 vcc, exec, s[66:67]
	s_cbranch_vccz .LBB0_67
	s_barrier

.Lmy_peel:
	s_add_i32 s33, s42, 2
	s_add_u32 s46, s40, 0x80
	s_addc_u32 s43, s41, 0
	s_add_i32 s80, 0, 0x10000
	s_cmp_eq_u32 s84, s42
	s_cselect_b32 s43, s1, s43
	s_cselect_b32 s42, s0, s46
	s_cselect_b32 s47, s75, vcc_hi
	s_cselect_b32 s46, s74, vcc_lo
	s_add_i32 s5, 0, 0x14000
	v_add_u32_e32 v140, s80, v185
	v_add_u32_e32 v166, s5, v185
	ds_read_b128 v[128:131], v140
	ds_read_b128 v[132:135], v140 offset:1024
	ds_read_b128 v[136:139], v140 offset:2048
	ds_read_b128 v[140:143], v140 offset:3072
	ds_read_b128 v[144:147], v166
	ds_read_b128 v[148:151], v166 offset:1024
	ds_read_b128 v[152:155], v166 offset:2048
	ds_read_b128 v[166:169], v166 offset:3072
	v_lshl_add_u64 v[182:183], s[40:41], 0, v[162:163]
	s_add_i32 m0, s28, 0xc000
	ds_read_b128 v[170:173], v188
	ds_read_b128 v[174:177], v188 offset:1024
	ds_read_b128 v[178:181], v188 offset:2048
	ds_read_b128 v[214:217], v188 offset:3072
	ds_read_b128 v[218:221], v188 offset:4096
	ds_read_b128 v[222:225], v188 offset:5120
	ds_read_b128 v[226:229], v188 offset:6144
	ds_read_b128 v[230:233], v188 offset:7168
	global_load_lds_dwordx4 v[182:183], off
	v_lshl_add_u64 v[182:183], s[40:41], 0, v[164:165]
	s_add_i32 m0, s28, 0xe000
	s_nop 0
	global_load_lds_dwordx4 v[182:183], off
	s_waitcnt vmcnt(24)
	s_barrier
	s_waitcnt lgkmcnt(0)
	v_mfma_f32_16x16x32_bf16 v[124:127], v[128:131], v[170:173], 0
	v_mfma_f32_16x16x32_bf16 v[120:123], v[136:139], v[170:173], 0
	v_mfma_f32_16x16x32_bf16 v[108:111], v[128:131], v[178:181], 0
	v_mfma_f32_16x16x32_bf16 v[104:107], v[136:139], v[178:181], 0
	v_mfma_f32_16x16x32_bf16 v[92:95], v[128:131], v[218:221], 0
	v_mfma_f32_16x16x32_bf16 v[88:91], v[136:139], v[218:221], 0
	v_mfma_f32_16x16x32_bf16 v[76:79], v[128:131], v[226:229], 0
	v_mfma_f32_16x16x32_bf16 v[72:75], v[136:139], v[226:229], 0
	v_mfma_f32_16x16x32_bf16 v[124:127], v[132:135], v[174:177], v[124:127]
	v_mfma_f32_16x16x32_bf16 v[120:123], v[140:143], v[174:177], v[120:123]
	v_mfma_f32_16x16x32_bf16 v[108:111], v[132:135], v[214:217], v[108:111]
	v_mfma_f32_16x16x32_bf16 v[104:107], v[140:143], v[214:217], v[104:107]
	v_mfma_f32_16x16x32_bf16 v[92:95], v[132:135], v[222:225], v[92:95]
	v_mfma_f32_16x16x32_bf16 v[88:91], v[140:143], v[222:225], v[88:91]
	v_mfma_f32_16x16x32_bf16 v[76:79], v[132:135], v[230:233], v[76:79]
	v_mfma_f32_16x16x32_bf16 v[72:75], v[140:143], v[230:233], v[72:75]
	v_mfma_f32_16x16x32_bf16 v[116:119], v[144:147], v[170:173], 0
	v_mfma_f32_16x16x32_bf16 v[112:115], v[152:155], v[170:173], 0
	v_mfma_f32_16x16x32_bf16 v[100:103], v[144:147], v[178:181], 0
	v_mfma_f32_16x16x32_bf16 v[96:99], v[152:155], v[178:181], 0
	v_mfma_f32_16x16x32_bf16 v[84:87], v[144:147], v[218:221], 0
	v_mfma_f32_16x16x32_bf16 v[80:83], v[152:155], v[218:221], 0
	v_mfma_f32_16x16x32_bf16 v[68:71], v[144:147], v[226:229], 0
	v_mfma_f32_16x16x32_bf16 v[64:67], v[152:155], v[226:229], 0
	v_mfma_f32_16x16x32_bf16 v[116:119], v[148:151], v[174:177], v[116:119]
	v_mfma_f32_16x16x32_bf16 v[112:115], v[166:169], v[174:177], v[112:115]
	v_mfma_f32_16x16x32_bf16 v[100:103], v[148:151], v[214:217], v[100:103]
	v_mfma_f32_16x16x32_bf16 v[96:99], v[166:169], v[214:217], v[96:99]
	v_mfma_f32_16x16x32_bf16 v[84:87], v[148:151], v[222:225], v[84:87]
	v_mfma_f32_16x16x32_bf16 v[80:83], v[166:169], v[222:225], v[80:83]
	v_mfma_f32_16x16x32_bf16 v[68:71], v[148:151], v[230:233], v[68:71]
	v_mfma_f32_16x16x32_bf16 v[64:67], v[166:169], v[230:233], v[64:67]
	s_barrier
	s_add_i32 s80, s80, s27
	v_lshl_add_u64 v[182:183], s[46:47], 0, v[192:193]
	s_mov_b32 m0, s80
	ds_read_b128 v[170:173], v188 offset:16384
	ds_read_b128 v[174:177], v188 offset:17408
	ds_read_b128 v[178:181], v188 offset:18432
	ds_read_b128 v[214:217], v188 offset:19456
	ds_read_b128 v[218:221], v188 offset:20480
	ds_read_b128 v[222:225], v188 offset:21504
	ds_read_b128 v[226:229], v188 offset:22528
	ds_read_b128 v[230:233], v188 offset:23552
	global_load_lds_dwordx4 v[182:183], off
	s_add_i32 m0, s80, 0x2000
	v_lshl_add_u64 v[190:191], s[46:47], 0, v[160:161]
	s_add_u32 s46, s46, s30
	s_addc_u32 s47, s47, 0
	s_add_i32 s5, s5, s27
	global_load_lds_dwordx4 v[190:191], off
	v_lshl_add_u64 v[200:201], s[46:47], 0, v[192:193]
	s_mov_b32 m0, s5
	v_lshl_add_u64 v[234:235], s[46:47], 0, v[160:161]
	global_load_lds_dwordx4 v[200:201], off
	s_add_i32 m0, s5, 0x2000
	v_lshl_add_u64 v[236:237], s[42:43], 0, v[156:157]
	global_load_lds_dwordx4 v[234:235], off
	s_mov_b32 m0, s28
	v_lshl_add_u64 v[238:239], s[42:43], 0, v[158:159]
	global_load_lds_dwordx4 v[236:237], off
	s_mov_b32 m0, s69
	s_nop 0
	global_load_lds_dwordx4 v[238:239], off
	s_waitcnt vmcnt(24)
	s_barrier
	s_waitcnt lgkmcnt(0)
	v_mfma_f32_16x16x32_bf16 v[60:63], v[128:131], v[170:173], 0
	v_mfma_f32_16x16x32_bf16 v[56:59], v[136:139], v[170:173], 0
	v_mfma_f32_16x16x32_bf16 v[44:47], v[128:131], v[178:181], 0
	v_mfma_f32_16x16x32_bf16 v[40:43], v[136:139], v[178:181], 0
	v_mfma_f32_16x16x32_bf16 v[28:31], v[128:131], v[218:221], 0
	v_mfma_f32_16x16x32_bf16 v[24:27], v[136:139], v[218:221], 0
	v_mfma_f32_16x16x32_bf16 v[12:15], v[128:131], v[226:229], 0
	v_mfma_f32_16x16x32_bf16 v[8:11], v[136:139], v[226:229], 0
	v_mfma_f32_16x16x32_bf16 v[60:63], v[132:135], v[174:177], v[60:63]
	v_mfma_f32_16x16x32_bf16 v[56:59], v[140:143], v[174:177], v[56:59]
	v_mfma_f32_16x16x32_bf16 v[44:47], v[132:135], v[214:217], v[44:47]
	v_mfma_f32_16x16x32_bf16 v[40:43], v[140:143], v[214:217], v[40:43]
	v_mfma_f32_16x16x32_bf16 v[28:31], v[132:135], v[222:225], v[28:31]
	v_mfma_f32_16x16x32_bf16 v[24:27], v[140:143], v[222:225], v[24:27]
	v_mfma_f32_16x16x32_bf16 v[12:15], v[132:135], v[230:233], v[12:15]
	v_mfma_f32_16x16x32_bf16 v[8:11], v[140:143], v[230:233], v[8:11]
	v_mfma_f32_16x16x32_bf16 v[52:55], v[144:147], v[170:173], 0
	v_mfma_f32_16x16x32_bf16 v[48:51], v[152:155], v[170:173], 0
	v_mfma_f32_16x16x32_bf16 v[36:39], v[144:147], v[178:181], 0
	v_mfma_f32_16x16x32_bf16 v[32:35], v[152:155], v[178:181], 0
	v_mfma_f32_16x16x32_bf16 v[20:23], v[144:147], v[218:221], 0
	v_mfma_f32_16x16x32_bf16 v[16:19], v[152:155], v[218:221], 0
	v_mfma_f32_16x16x32_bf16 v[4:7], v[144:147], v[226:229], 0
	v_mfma_f32_16x16x32_bf16 v[0:3], v[152:155], v[226:229], 0
	v_mfma_f32_16x16x32_bf16 v[52:55], v[148:151], v[174:177], v[52:55]
	v_mfma_f32_16x16x32_bf16 v[48:51], v[166:169], v[174:177], v[48:51]
	v_mfma_f32_16x16x32_bf16 v[36:39], v[148:151], v[214:217], v[36:39]
	v_mfma_f32_16x16x32_bf16 v[32:35], v[166:169], v[214:217], v[32:35]
	v_mfma_f32_16x16x32_bf16 v[20:23], v[148:151], v[222:225], v[20:23]
	v_mfma_f32_16x16x32_bf16 v[16:19], v[166:169], v[222:225], v[16:19]
	v_mfma_f32_16x16x32_bf16 v[4:7], v[148:151], v[230:233], v[4:7]
	v_mfma_f32_16x16x32_bf16 v[0:3], v[166:169], v[230:233], v[0:3]
	s_barrier
	s_branch .Lmy_sp3
